# scan loader conversion on two register sets: every even prompt iteration plus every fourth odd one starts a weight tile (96 per loader wave and scan phase instead of 64), so chain 2's weights are also
# baseline (speedup 1.0000x reference)
.LBB0_1621:
	s_waitcnt lgkmcnt(0)
	s_add_u32 s14, s8, 0x3fa00000
	s_addc_u32 s15, s9, 0
	s_waitcnt lgkmcnt(0)
	s_barrier
	s_cmp_gt_i32 s40, 0
	v_and_b32_e32 v38, 15, v173
	s_cselect_b64 s[20:21], -1, 0
	s_cmp_lt_i32 s40, 1
	v_lshlrev_b32_e32 v40, 2, v43
	s_cbranch_scc1 .LBB0_1658
	s_lshl_b64 s[22:23], s[90:91], 11
	s_lshl_b64 s[24:25], s[90:91], 6
	s_add_i32 s3, 0, 0x1c000
	s_add_i32 s52, 0, 0x18000
	s_add_i32 s41, s40, -1
	s_add_u32 s42, s8, 0x33400000
	s_addc_u32 s43, s9, 0
	v_lshrrev_b32_e32 v0, 4, v2
	s_add_u32 s44, s8, 0x586c0000
	v_lshl_or_b32 v58, s2, 2, v0
	s_addc_u32 s45, s9, 0
	v_lshlrev_b32_e32 v0, 4, v58
	v_and_b32_e32 v2, 12, v38
	s_add_u32 s46, s8, 0x4c6c0000
	v_add3_u32 v59, s3, v0, v2
	v_lshlrev_b32_e32 v0, 8, v58
	v_lshlrev_b32_e32 v2, 4, v38
	s_addc_u32 s48, s9, 0
	s_lshl_b32 s2, s2, 10
	v_add3_u32 v60, s52, v0, v2
	s_add_i32 s49, s2, 0
	s_add_i32 s52, s52, s2
	v_readlane_b32 s2, v253, 53
	v_mov_b32_e32 v41, v1
	v_lshl_add_u32 v61, v43, 4, s3
	s_mul_i32 s2, s2, s38
	v_readlane_b32 s3, v253, 52
	v_lshlrev_b32_e32 v0, 6, v58
	v_lshl_add_u64 v[44:45], s[14:15], 0, v[40:41]
	v_lshrrev_b32_e32 v41, 4, v43
	s_sub_i32 s54, s3, s2
	s_not_b32 s2, s38
	v_readlane_b32 s3, v253, 2
	v_lshlrev_b32_e32 v42, 2, v38
	v_lshlrev_b32_e32 v46, 12, v41
	v_mov_b32_e32 v47, v1
	s_mul_i32 s55, s3, s2
	v_mov_b32_e32 v2, v1
	v_mov_b32_e32 v3, v1
	v_mov_b32_e32 v4, v1
	v_mov_b32_e32 v5, v1
	s_mov_b32 s57, 0
	s_movk_i32 s58, 0xf000
	s_movk_i32 s59, 0xc000
	v_lshlrev_b32_e32 v48, 2, v0
	v_lshlrev_b32_e32 v0, 2, v40
	v_lshlrev_b32_e32 v50, 2, v38
	v_readlane_b32 s60, v253, 3
	s_load_dwordx2 s[64:65], s[0:1], 0x1a8
	s_load_dwordx2 s[70:71], s[0:1], 0x10
	s_waitcnt lgkmcnt(0)
	s_add_i32 s98, s47, 0x20180
	v_mov_b32_e32 v111, s98
	ds_read_b64 v[112:113], v111
	v_and_b32_e32 v114, 7, v173
	v_bfe_u32 v115, v173, 3, 3
	v_mul_u32_u24_e32 v106, 0x2c000, v115
	v_lshl_add_u32 v106, v114, 4, v106
	v_lshlrev_b32_e32 v107, 16, v115
	v_lshl_add_u32 v107, v114, 4, v107
	v_lshlrev_b32_e32 v108, 14, v114
	v_lshl_add_u32 v108, v115, 4, v108
	v_mul_u32_u24_e32 v109, 0xb000, v114
	v_lshl_add_u32 v109, v115, 4, v109
	v_lshlrev_b32_e32 v110, 5, v115
	s_add_i32 s99, s98, -32
	v_mov_b32_e32 v120, s99
	ds_read_b64 v[118:119], v120
	s_mov_b32 s94, 0
	s_mov_b32 s95, 0
	s_waitcnt lgkmcnt(0)
	v_readfirstlane_b32 s2, v112
	v_readfirstlane_b32 s3, v113
	v_readfirstlane_b32 s92, v118
	v_readfirstlane_b32 s93, v119
	s_mov_b32 s4, 1
	s_mov_b32 s5, 0
	v_writelane_b32 v117, s2, 0
	v_writelane_b32 v117, s3, 1
	v_writelane_b32 v117, s4, 2
	v_writelane_b32 v117, s5, 3
	s_mov_b32 s2, 0
	s_nop 0
	v_writelane_b32 v117, s2, 6
	s_branch .LBB0_1625
.LBB0_1623:
	s_cmp_eq_u32 s57, 0
	s_cbranch_scc1 .Lcv_w0
	s_waitcnt vmcnt(30)
	s_branch .Lcv_w1
.Lcv_w0:
	s_waitcnt vmcnt(15)
.Lcv_w1:
	s_bitcmp1_b32 s57, 0
	s_cbranch_scc1 .Lcv1_w1
.Lcv0_w1:
	s_cmp_lt_u32 s94, 2
	s_cbranch_scc1 .Lcv0_b_notitem
	s_cmp_eq_u32 s94, 2
	s_cbranch_scc1 .Lcv0_b_scale
	s_cmp_eq_u32 s94, 5
	s_cbranch_scc0 .Lcv0_b_cvt

.Lcv0_b_notitem:
	global_store_dword v[44:45], v1, off
	global_store_dword v[44:45], v1, off
	global_store_dword v[44:45], v1, off
	global_store_dword v[44:45], v1, off
	s_cmp_eq_u32 s94, 1
	s_cbranch_scc0 .Lcv0_b_done
	v_readfirstlane_b32 s2, v113
	s_add_i32 s92, s2, 0x5720
	s_sub_i32 s93, 0x27e40, s92
	s_min_i32 s93, s93, 16
	s_cmp_gt_i32 s93, 0
	s_cselect_b32 s93, s93, -1
	s_mov_b32 s2, 0
	s_nop 0
	v_writelane_b32 v117, s2, 6

.Lcv0_a_top:
	s_cmp_gt_i32 s93, 0
	s_cbranch_scc1 .Lcv0_a_item
	v_readlane_b32 s2, v117, 2
	s_cmp_eq_u32 s2, 1
	s_cbranch_scc1 .Lcv0_switch
	s_cmp_lt_i32 s93, 0
	s_cbranch_scc1 .Lcv0_a_stop
	v_readlane_b32 s2, v117, 6
	s_cmp_eq_u32 s2, 1
	s_cbranch_scc1 .Lcv0_pad10
	s_load_dwordx2 s[2:3], s[0:1], 0x1b0
	v_mov_b32_e32 v113, 16
	s_waitcnt lgkmcnt(0)
	s_add_u32 s2, s2, 0x1000
	s_addc_u32 s3, s3, 0
	s_mov_b64 exec, 1
	global_atomic_add v113, v1, v113, s[2:3] sc0
	s_mov_b64 exec, -1
	s_mov_b32 s94, 1
	s_mov_b32 s2, 1
	s_nop 0
	v_writelane_b32 v117, s2, 6
	s_branch .Lcv0_pad9

.Lcv0_switch:
	s_add_i32 s2, s47, 0x20160
	v_mov_b32_e32 v111, s2
	v_mov_b32_e32 v112, s92
	v_mov_b32_e32 v121, s93
	s_mov_b64 exec, 1
	ds_write2_b32 v111, v112, v121 offset1:1
	s_mov_b64 exec, -1
	v_readlane_b32 s92, v117, 0
	v_readlane_b32 s93, v117, 1
	s_mov_b32 s2, 0
	s_nop 0
	v_writelane_b32 v117, s2, 2
	s_branch .Lcv0_a_top

.Lcv0_sq:
	s_lshr_b32 s91, s3, 6
	s_and_b32 s2, s3, 63
	s_lshl_b32 s56, s91, 19
	s_add_u32 s61, s61, s56
	s_lshl_b32 s56, s2, 7
	s_add_u32 s61, s61, s56
	s_lshl_b32 s56, s2, 17
	s_add_u32 s66, s66, s56
	s_lshl_b32 s56, s91, 7
	s_add_u32 s66, s66, s56
	s_load_dwordx2 s[32:33], s[0:1], s5
	s_load_dwordx2 s[98:99], s[0:1], 0x1b0
	s_cmp_eq_u32 s18, 0
	s_cbranch_scc1 .Lcv0_sq_ns
	s_lshl_b32 s56, s91, 8
	s_add_i32 s62, s62, s56
	s_load_dwordx2 s[2:3], s[0:1], 0x98
	s_waitcnt lgkmcnt(0)
	s_add_u32 s2, s2, s62
	s_addc_u32 s3, s3, 0
	s_nop 0
	global_load_dwordx4 v[162:165], v110, s[2:3]
	global_load_dwordx4 v[166:169], v110, s[2:3] offset:16
	s_mov_b32 s18, 5
	s_branch .Lcv0_sq_ld
.Lcv0_sq_ns:
	s_waitcnt lgkmcnt(0)
	s_mov_b32 s18, 4
.Lcv0_sq_ld:
	s_add_u32 s32, s32, s61
	s_addc_u32 s33, s33, 0
	s_add_u32 s96, s98, s66
	s_addc_u32 s97, s99, 0
	s_nop 0
	global_load_dwordx4 v[130:133], v107, s[32:33] nt
	s_add_u32 s32, s32, 0x2000
	s_addc_u32 s33, s33, 0
	s_nop 0
	global_load_dwordx4 v[134:137], v107, s[32:33] nt
	s_add_u32 s32, s32, 0x2000
	s_addc_u32 s33, s33, 0
	s_nop 0
	global_load_dwordx4 v[138:141], v107, s[32:33] nt
	s_add_u32 s32, s32, 0x2000
	s_addc_u32 s33, s33, 0
	s_nop 0
	global_load_dwordx4 v[142:145], v107, s[32:33] nt
	s_add_u32 s32, s32, 0x2000
	s_addc_u32 s33, s33, 0
	s_nop 0
	global_load_dwordx4 v[146:149], v107, s[32:33] nt
	s_add_u32 s32, s32, 0x2000
	s_addc_u32 s33, s33, 0
	s_nop 0
	global_load_dwordx4 v[150:153], v107, s[32:33] nt
	s_add_u32 s32, s32, 0x2000
	s_addc_u32 s33, s33, 0
	s_nop 0
	global_load_dwordx4 v[154:157], v107, s[32:33] nt
	s_add_u32 s32, s32, 0x2000
	s_addc_u32 s33, s33, 0
	s_nop 0
	global_load_dwordx4 v[158:161], v107, s[32:33] nt
	s_mov_b32 s94, s18
	s_add_i32 s92, s92, 1
	s_sub_i32 s93, s93, 1
	s_cmp_eq_u32 s18, 5
	s_cbranch_scc1 .Lcv0_pad0
	s_branch .Lcv0_pad2

.Lcv1_w1:
	v_readlane_b32 s56, v117, 3
	v_readlane_b32 s32, v117, 4
	v_readlane_b32 s33, v117, 5
	s_cmp_lt_u32 s56, 2
	s_cbranch_scc1 .Lcv1_b_notitem
	s_cmp_eq_u32 s56, 2
	s_cbranch_scc1 .Lcv1_b_scale
	s_cmp_eq_u32 s56, 5
	s_cbranch_scc0 .Lcv1_b_cvt
.Lcv1_b_scale:
	v_pk_mul_f32 v[62:63], v[62:63], v[94:95] op_sel_hi:[1,0]
	v_pk_mul_f32 v[64:65], v[64:65], v[94:95] op_sel_hi:[1,0]
	v_pk_mul_f32 v[66:67], v[66:67], v[94:95] op_sel:[0,1] op_sel_hi:[1,1]
	v_pk_mul_f32 v[68:69], v[68:69], v[94:95] op_sel:[0,1] op_sel_hi:[1,1]
	v_pk_mul_f32 v[70:71], v[70:71], v[96:97] op_sel_hi:[1,0]
	v_pk_mul_f32 v[72:73], v[72:73], v[96:97] op_sel_hi:[1,0]
	v_pk_mul_f32 v[74:75], v[74:75], v[96:97] op_sel:[0,1] op_sel_hi:[1,1]
	v_pk_mul_f32 v[76:77], v[76:77], v[96:97] op_sel:[0,1] op_sel_hi:[1,1]
	v_pk_mul_f32 v[78:79], v[78:79], v[98:99] op_sel_hi:[1,0]
	v_pk_mul_f32 v[80:81], v[80:81], v[98:99] op_sel_hi:[1,0]
	v_pk_mul_f32 v[82:83], v[82:83], v[98:99] op_sel:[0,1] op_sel_hi:[1,1]
	v_pk_mul_f32 v[84:85], v[84:85], v[98:99] op_sel:[0,1] op_sel_hi:[1,1]
	v_pk_mul_f32 v[86:87], v[86:87], v[100:101] op_sel_hi:[1,0]
	v_pk_mul_f32 v[88:89], v[88:89], v[100:101] op_sel_hi:[1,0]
	v_pk_mul_f32 v[90:91], v[90:91], v[100:101] op_sel:[0,1] op_sel_hi:[1,1]
	v_pk_mul_f32 v[92:93], v[92:93], v[100:101] op_sel:[0,1] op_sel_hi:[1,1]
.Lcv1_b_cvt:
	v_cvt_pk_bf16_f32 v18, v62, v66
	v_cvt_pk_bf16_f32 v19, v70, v74
	v_cvt_pk_bf16_f32 v20, v78, v82
	v_cvt_pk_bf16_f32 v21, v86, v90
	v_cvt_pk_bf16_f32 v22, v63, v67
	v_cvt_pk_bf16_f32 v23, v71, v75
	v_cvt_pk_bf16_f32 v24, v79, v83
	v_cvt_pk_bf16_f32 v25, v87, v91
	v_cvt_pk_bf16_f32 v26, v64, v68
	v_cvt_pk_bf16_f32 v27, v72, v76
	v_cvt_pk_bf16_f32 v28, v80, v84
	v_cvt_pk_bf16_f32 v29, v88, v92
	v_cvt_pk_bf16_f32 v30, v65, v69
	v_cvt_pk_bf16_f32 v31, v73, v77
	v_cvt_pk_bf16_f32 v32, v81, v85
	v_cvt_pk_bf16_f32 v33, v89, v93
	s_cmp_eq_u32 s56, 3
	s_cbranch_scc1 .Lcv1_b_st1
	global_store_dwordx4 v108, v[18:21], s[32:33]
	s_add_u32 s32, s32, 0x1000
	s_addc_u32 s33, s33, 0
	s_nop 0
	global_store_dwordx4 v108, v[22:25], s[32:33]
	s_add_u32 s32, s32, 0x1000
	s_addc_u32 s33, s33, 0
	s_nop 0
	global_store_dwordx4 v108, v[26:29], s[32:33]
	s_add_u32 s32, s32, 0x1000
	s_addc_u32 s33, s33, 0
	s_nop 0
	global_store_dwordx4 v108, v[30:33], s[32:33]
	s_branch .Lcv1_b_done
.Lcv1_b_st1:
	global_store_dwordx4 v109, v[18:21], s[32:33]
	s_add_u32 s32, s32, 0x2c00
	s_addc_u32 s33, s33, 0
	s_nop 0
	global_store_dwordx4 v109, v[22:25], s[32:33]
	s_add_u32 s32, s32, 0x2c00
	s_addc_u32 s33, s33, 0
	s_nop 0
	global_store_dwordx4 v109, v[26:29], s[32:33]
	s_add_u32 s32, s32, 0x2c00
	s_addc_u32 s33, s33, 0
	s_nop 0
	global_store_dwordx4 v109, v[30:33], s[32:33]
	s_branch .Lcv1_b_done
.Lcv1_b_notitem:
	global_store_dword v[44:45], v1, off
	global_store_dword v[44:45], v1, off
	global_store_dword v[44:45], v1, off
	global_store_dword v[44:45], v1, off
	s_cmp_eq_u32 s56, 1
	s_cbranch_scc0 .Lcv1_b_done
	v_readfirstlane_b32 s2, v113
	s_add_i32 s92, s2, 0x5720
	s_sub_i32 s93, 0x27e40, s92
	s_min_i32 s93, s93, 16
	s_cmp_gt_i32 s93, 0
	s_cselect_b32 s93, s93, -1
	s_mov_b32 s2, 0
	s_nop 0
	v_writelane_b32 v117, s2, 6
.Lcv1_b_done:
	s_mov_b32 s4, 0
	s_nop 0
	v_writelane_b32 v117, s4, 3
	s_cmp_eq_u32 s95, 2
	s_cbranch_scc1 .Lcv_drain_ret1
	s_cmp_lg_u32 s95, 0
	s_cbranch_scc1 .Lcv1_pad10
	s_cmp_ge_i32 s57, s38
	s_cbranch_scc1 .Lcv1_pad10
	s_and_b32 s2, s57, 3
	s_cmp_lg_u32 s2, 1
	s_cbranch_scc1 .Lcv1_pad10
.Lcv1_a_top:
	s_cmp_gt_i32 s93, 0
	s_cbranch_scc1 .Lcv1_a_item
	v_readlane_b32 s2, v117, 2
	s_cmp_eq_u32 s2, 1
	s_cbranch_scc1 .Lcv1_switch
	s_cmp_lt_i32 s93, 0
	s_cbranch_scc1 .Lcv1_a_stop
	v_readlane_b32 s2, v117, 6
	s_cmp_eq_u32 s2, 1
	s_cbranch_scc1 .Lcv1_pad10
	s_load_dwordx2 s[2:3], s[0:1], 0x1b0
	v_mov_b32_e32 v113, 16
	s_waitcnt lgkmcnt(0)
	s_add_u32 s2, s2, 0x1000
	s_addc_u32 s3, s3, 0
	s_mov_b64 exec, 1
	global_atomic_add v113, v1, v113, s[2:3] sc0
	s_mov_b64 exec, -1
	s_mov_b32 s4, 1
	s_nop 0
	v_writelane_b32 v117, s4, 3
	s_mov_b32 s2, 1
	s_nop 0
	v_writelane_b32 v117, s2, 6
	s_branch .Lcv1_pad9

.Lcv1_seg:
	s_cmp_lt_u32 s3, 0x2c00
	s_cbranch_scc0 .Lcv1_k1
	s_cmp_ge_u32 s3, 0x1600
	s_cselect_b32 s18, 1, 0
	s_cselect_b32 s2, 0x1600, 0
	s_sub_i32 s3, s3, s2
	s_mul_i32 s91, s3, 0x1746
	s_lshr_b32 s91, s91, 20
	s_mul_i32 s4, s91, 0xb0
	s_sub_i32 s4, s3, s4
	s_lshr_b32 s2, s5, 1
	s_mul_i32 s61, s2, 0x2c00000
	s_lshl_b32 s62, s2, 13
	s_and_b32 s56, s5, 1
	s_mul_i32 s56, s56, 40
	s_mul_i32 s2, s91, 0x160000
	s_add_u32 s61, s61, s2
	s_lshl_b32 s2, s4, 7
	s_add_u32 s61, s61, s2
	s_lshl_b32 s2, s91, 8
	s_add_i32 s62, s62, s2
	s_lshr_b32 s66, s4, 2
	s_lshl_b32 s66, s66, 8
	s_and_b32 s2, s4, 3
	s_lshl_b32 s2, s2, 5
	s_add_i32 s66, s66, s2
	s_lshl_b32 s2, s18, 7
	s_add_i32 s66, s66, s2
	s_lshl_b32 s66, s66, 12
	s_mul_i32 s2, s5, 0x2c00000
	s_add_u32 s66, s66, s2
	s_add_u32 s66, s66, 0x200000
	s_lshl_b32 s2, s91, 7
	s_add_u32 s66, s66, s2
	s_lshl_b32 s4, s18, 3
	s_add_i32 s4, s4, s56
	s_add_i32 s4, s4, 0x58
	s_add_i32 s56, s56, 0x50
	s_load_dwordx2 s[32:33], s[0:1], s4
	s_load_dwordx2 s[2:3], s[0:1], s56
	s_load_dwordx2 s[98:99], s[0:1], 0x1b0
	s_waitcnt lgkmcnt(0)
	s_add_u32 s32, s32, s61
	s_addc_u32 s33, s33, 0
	s_add_u32 s2, s2, s62
	s_addc_u32 s3, s3, 0
	s_add_u32 s4, s98, s66
	s_addc_u32 s5, s99, 0
	s_nop 0
	v_writelane_b32 v117, s4, 4
	v_writelane_b32 v117, s5, 5
	s_nop 0
	global_load_dwordx4 v[94:97], v110, s[2:3]
	global_load_dwordx4 v[98:101], v110, s[2:3] offset:16
	global_load_dwordx4 v[62:65], v106, s[32:33] nt
	s_add_u32 s32, s32, 0x5800
	s_addc_u32 s33, s33, 0
	s_nop 0
	global_load_dwordx4 v[66:69], v106, s[32:33] nt
	s_add_u32 s32, s32, 0x5800
	s_addc_u32 s33, s33, 0
	s_nop 0
	global_load_dwordx4 v[70:73], v106, s[32:33] nt
	s_add_u32 s32, s32, 0x5800
	s_addc_u32 s33, s33, 0
	s_nop 0
	global_load_dwordx4 v[74:77], v106, s[32:33] nt
	s_add_u32 s32, s32, 0x5800
	s_addc_u32 s33, s33, 0
	s_nop 0
	global_load_dwordx4 v[78:81], v106, s[32:33] nt
	s_add_u32 s32, s32, 0x5800
	s_addc_u32 s33, s33, 0
	s_nop 0
	global_load_dwordx4 v[82:85], v106, s[32:33] nt
	s_add_u32 s32, s32, 0x5800
	s_addc_u32 s33, s33, 0
	s_nop 0
	global_load_dwordx4 v[86:89], v106, s[32:33] nt
	s_add_u32 s32, s32, 0x5800
	s_addc_u32 s33, s33, 0
	s_nop 0
	global_load_dwordx4 v[90:93], v106, s[32:33] nt
	s_mov_b32 s4, 2
	s_nop 0
	v_writelane_b32 v117, s4, 3
	s_add_i32 s92, s92, 1
	s_sub_i32 s93, s93, 1
	s_branch .Lcv1_pad0
.Lcv1_k1:
	s_sub_i32 s3, s3, 0x2c00
	s_lshr_b32 s91, s3, 6
	s_and_b32 s4, s3, 63
	s_lshr_b32 s2, s5, 1
	s_mul_i32 s61, s2, 0x2c00000
	s_lshl_b32 s2, s91, 19
	s_add_u32 s61, s61, s2
	s_lshl_b32 s2, s4, 7
	s_add_u32 s61, s61, s2
	s_mul_i32 s66, s5, 0x1600000
	s_add_u32 s66, s66, 0x16200000
	s_mul_i32 s2, s4, 0x58000
	s_add_u32 s66, s66, s2
	s_lshl_b32 s2, s91, 7
	s_add_u32 s66, s66, s2
	s_and_b32 s4, s5, 1
	s_mul_i32 s4, s4, 40
	s_add_i32 s4, s4, 0x68
	s_load_dwordx2 s[32:33], s[0:1], s4
	s_load_dwordx2 s[98:99], s[0:1], 0x1b0
	s_waitcnt lgkmcnt(0)
	s_add_u32 s32, s32, s61
	s_addc_u32 s33, s33, 0
	s_add_u32 s4, s98, s66
	s_addc_u32 s5, s99, 0
	s_nop 0
	v_writelane_b32 v117, s4, 4
	v_writelane_b32 v117, s5, 5
	s_nop 0
	global_load_dwordx4 v[62:65], v107, s[32:33] nt
	s_add_u32 s32, s32, 0x2000
	s_addc_u32 s33, s33, 0
	s_nop 0
	global_load_dwordx4 v[66:69], v107, s[32:33] nt
	s_add_u32 s32, s32, 0x2000
	s_addc_u32 s33, s33, 0
	s_nop 0
	global_load_dwordx4 v[70:73], v107, s[32:33] nt
	s_add_u32 s32, s32, 0x2000
	s_addc_u32 s33, s33, 0
	s_nop 0
	global_load_dwordx4 v[74:77], v107, s[32:33] nt
	s_add_u32 s32, s32, 0x2000
	s_addc_u32 s33, s33, 0
	s_nop 0
	global_load_dwordx4 v[78:81], v107, s[32:33] nt
	s_add_u32 s32, s32, 0x2000
	s_addc_u32 s33, s33, 0
	s_nop 0
	global_load_dwordx4 v[82:85], v107, s[32:33] nt
	s_add_u32 s32, s32, 0x2000
	s_addc_u32 s33, s33, 0
	s_nop 0
	global_load_dwordx4 v[86:89], v107, s[32:33] nt
	s_add_u32 s32, s32, 0x2000
	s_addc_u32 s33, s33, 0
	s_nop 0
	global_load_dwordx4 v[90:93], v107, s[32:33] nt
	s_mov_b32 s4, 3
	s_nop 0
	v_writelane_b32 v117, s4, 3
	s_add_i32 s92, s92, 1
	s_sub_i32 s93, s93, 1
	s_branch .Lcv1_pad2

.Lcv1_sq:
	s_lshr_b32 s91, s3, 6
	s_and_b32 s2, s3, 63
	s_lshl_b32 s56, s91, 19
	s_add_u32 s61, s61, s56
	s_lshl_b32 s56, s2, 7
	s_add_u32 s61, s61, s56
	s_lshl_b32 s56, s2, 17
	s_add_u32 s66, s66, s56
	s_lshl_b32 s56, s91, 7
	s_add_u32 s66, s66, s56
	s_load_dwordx2 s[32:33], s[0:1], s5
	s_load_dwordx2 s[98:99], s[0:1], 0x1b0
	s_cmp_eq_u32 s18, 0
	s_cbranch_scc1 .Lcv1_sq_ns
	s_lshl_b32 s56, s91, 8
	s_add_i32 s62, s62, s56
	s_load_dwordx2 s[2:3], s[0:1], 0x98
	s_waitcnt lgkmcnt(0)
	s_add_u32 s2, s2, s62
	s_addc_u32 s3, s3, 0
	s_nop 0
	global_load_dwordx4 v[94:97], v110, s[2:3]
	global_load_dwordx4 v[98:101], v110, s[2:3] offset:16
	s_mov_b32 s18, 5
	s_branch .Lcv1_sq_ld

.Lcv1_sq_ld:
	s_add_u32 s32, s32, s61
	s_addc_u32 s33, s33, 0
	s_add_u32 s4, s98, s66
	s_addc_u32 s5, s99, 0
	s_nop 0
	v_writelane_b32 v117, s4, 4
	v_writelane_b32 v117, s5, 5
	s_nop 0
	global_load_dwordx4 v[62:65], v107, s[32:33] nt
	s_add_u32 s32, s32, 0x2000
	s_addc_u32 s33, s33, 0
	s_nop 0
	global_load_dwordx4 v[66:69], v107, s[32:33] nt
	s_add_u32 s32, s32, 0x2000
	s_addc_u32 s33, s33, 0
	s_nop 0
	global_load_dwordx4 v[70:73], v107, s[32:33] nt
	s_add_u32 s32, s32, 0x2000
	s_addc_u32 s33, s33, 0
	s_nop 0
	global_load_dwordx4 v[74:77], v107, s[32:33] nt
	s_add_u32 s32, s32, 0x2000
	s_addc_u32 s33, s33, 0
	s_nop 0
	global_load_dwordx4 v[78:81], v107, s[32:33] nt
	s_add_u32 s32, s32, 0x2000
	s_addc_u32 s33, s33, 0
	s_nop 0
	global_load_dwordx4 v[82:85], v107, s[32:33] nt
	s_add_u32 s32, s32, 0x2000
	s_addc_u32 s33, s33, 0
	s_nop 0
	global_load_dwordx4 v[86:89], v107, s[32:33] nt
	s_add_u32 s32, s32, 0x2000
	s_addc_u32 s33, s33, 0
	s_nop 0
	global_load_dwordx4 v[90:93], v107, s[32:33] nt
	s_nop 0
	v_writelane_b32 v117, s18, 3
	s_add_i32 s92, s92, 1
	s_sub_i32 s93, s93, 1
	s_cmp_eq_u32 s18, 5
	s_cbranch_scc1 .Lcv1_pad0
	s_branch .Lcv1_pad2

.Lcv1_pad0:
	s_branch .Lcv_end
.Lcv_end:
	v_mov_b64_e32 v[36:37], v[4:5]
	v_mov_b64_e32 v[34:35], v[2:3]

.LBB0_1658:
	s_and_b64 vcc, exec, s[10:11]
	s_cbranch_vccz .Lcv_exit
	s_mov_b32 s95, 2
	s_waitcnt vmcnt(0)
	s_branch .Lcv0_w1
.Lcv_drain_ret0:
	s_branch .Lcv1_w1
.Lcv_drain_ret1:
	v_readlane_b32 s2, v117, 2
	s_lshl_b32 s2, s2, 5
	s_sub_i32 s2, 0x20180, s2
	s_add_i32 s2, s2, s47
	v_mov_b32_e32 v111, s2
	v_mov_b32_e32 v112, s92
	v_mov_b32_e32 v113, s93
	s_mov_b64 exec, 1
	ds_write_b64 v111, v[112:113]
	s_mov_b64 exec, -1
